# P1 k_rope tile loop copy also drops the fragment LDS reads that only fed the removed MFMAs, and all-padding waves skip their fragment reads
# baseline (speedup 1.0000x reference)
.Lkr_loop:
	s_and_b64 s[100:101], s[42:43], exec
	s_cbranch_scc0 .Lkr_dskip1
	ds_read_b128 v[128:131], v171
	ds_read_b128 v[132:135], v171 offset:1024
	ds_read_b128 v[160:163], v171 offset:2048
	ds_read_b128 v[164:167], v171 offset:3072
.Lkr_dskip1:
	s_add_u32 s11, s76, 0xfff80080
	s_addc_u32 s60, s77, -1
	s_cmp_eq_u32 s10, 28
	s_cselect_b32 s81, s45, s60
	s_cselect_b32 s80, s51, s11
	s_cselect_b32 s79, s49, vcc_hi
	s_cselect_b32 s78, s75, vcc_lo
	v_lshl_add_u64 v[168:169], s[76:77], 0, v[152:153]
	s_add_i32 m0, s82, 0xc000
	s_and_b64 s[100:101], s[42:43], exec
	s_cbranch_scc0 .Lkr_dskip2
	ds_read_b128 v[192:195], v173
	ds_read_b128 v[196:199], v173 offset:1024
	ds_read_b128 v[200:203], v173 offset:2048
	ds_read_b128 v[206:209], v173 offset:3072
	ds_read_b128 v[210:213], v173 offset:4096
	ds_read_b128 v[214:217], v173 offset:5120
	ds_read_b128 v[218:221], v173 offset:6144
	ds_read_b128 v[222:225], v173 offset:7168
.Lkr_dskip2:
	global_load_lds_dwordx4 v[168:169], off
	v_lshl_add_u64 v[168:169], s[76:77], 0, v[154:155]
	s_add_i32 m0, s82, 0xe000
	s_nop 0
	global_load_lds_dwordx4 v[168:169], off
	s_waitcnt vmcnt(8)
	s_waitcnt lgkmcnt(0)
	s_barrier
	s_setprio 1
	s_waitcnt lgkmcnt(0)
	s_and_b64 s[100:101], s[42:43], exec
	s_cbranch_scc0 .Lkr_skip1
	v_mfma_f32_16x16x32_bf16 v[124:127], v[128:131], v[192:195], v[124:127]
	v_mfma_f32_16x16x32_bf16 v[120:123], v[160:163], v[192:195], v[120:123]
	v_mfma_f32_16x16x32_bf16 v[116:119], v[128:131], v[200:203], v[116:119]
	v_mfma_f32_16x16x32_bf16 v[108:111], v[160:163], v[200:203], v[108:111]
	v_mfma_f32_16x16x32_bf16 v[100:103], v[128:131], v[210:213], v[100:103]
	v_mfma_f32_16x16x32_bf16 v[92:95], v[160:163], v[210:213], v[92:95]
	v_mfma_f32_16x16x32_bf16 v[84:87], v[128:131], v[218:221], v[84:87]
	v_mfma_f32_16x16x32_bf16 v[76:79], v[160:163], v[218:221], v[76:79]
	v_mfma_f32_16x16x32_bf16 v[124:127], v[132:135], v[196:199], v[124:127]
	v_mfma_f32_16x16x32_bf16 v[120:123], v[164:167], v[196:199], v[120:123]
	v_mfma_f32_16x16x32_bf16 v[116:119], v[132:135], v[206:209], v[116:119]
	v_mfma_f32_16x16x32_bf16 v[108:111], v[164:167], v[206:209], v[108:111]
	v_mfma_f32_16x16x32_bf16 v[100:103], v[132:135], v[214:217], v[100:103]
	v_mfma_f32_16x16x32_bf16 v[92:95], v[164:167], v[214:217], v[92:95]
	v_mfma_f32_16x16x32_bf16 v[84:87], v[132:135], v[222:225], v[84:87]
	v_mfma_f32_16x16x32_bf16 v[76:79], v[164:167], v[222:225], v[76:79]

.Lkr_skip2:
	s_setprio 0
	s_barrier
	s_add_i32 s11, s87, s3
	v_lshl_add_u64 v[168:169], s[78:79], 0, v[138:139]
	s_mov_b32 m0, s11
	s_and_b64 s[100:101], s[42:43], exec
	s_cbranch_scc0 .Lkr_dskip3
	ds_read_b128 v[192:195], v173 offset:16384
	ds_read_b128 v[196:199], v173 offset:17408
	ds_read_b128 v[200:203], v173 offset:18432
	ds_read_b128 v[206:209], v173 offset:19456
	ds_read_b128 v[210:213], v173 offset:20480
	ds_read_b128 v[214:217], v173 offset:21504
	ds_read_b128 v[218:221], v173 offset:22528
	ds_read_b128 v[222:225], v173 offset:23552
.Lkr_dskip3:
	global_load_lds_dwordx4 v[168:169], off
	s_add_i32 m0, s11, 0x2000
	s_add_u32 s60, s78, 0x80000
	v_lshl_add_u64 v[226:227], s[78:79], 0, v[142:143]
	s_addc_u32 s61, s79, 0
	s_add_i32 s11, s91, s3
	global_load_lds_dwordx4 v[226:227], off
	v_lshl_add_u64 v[228:229], s[60:61], 0, v[138:139]
	s_mov_b32 m0, s11
	v_lshl_add_u64 v[230:231], s[80:81], 0, v[140:141]
	global_load_lds_dwordx4 v[228:229], off
	v_lshl_add_u64 v[228:229], s[60:61], 0, v[142:143]
	s_add_i32 m0, s11, 0x2000
	s_nop 0
	global_load_lds_dwordx4 v[228:229], off
	v_lshl_add_u64 v[228:229], s[80:81], 0, v[136:137]
	s_mov_b32 m0, s82
	s_nop 0
	global_load_lds_dwordx4 v[228:229], off
	s_mov_b32 m0, s83
	s_nop 0
	global_load_lds_dwordx4 v[230:231], off
	s_waitcnt vmcnt(8)
	s_waitcnt lgkmcnt(0)
	s_barrier
	s_setprio 1
	s_waitcnt lgkmcnt(0)
	s_and_b64 s[100:101], s[42:43], exec
	s_cbranch_scc0 .Lkr_skip3
	v_mfma_f32_16x16x32_bf16 v[60:63], v[128:131], v[192:195], v[60:63]
	v_mfma_f32_16x16x32_bf16 v[56:59], v[160:163], v[192:195], v[56:59]
	v_mfma_f32_16x16x32_bf16 v[52:55], v[128:131], v[200:203], v[52:55]
	v_mfma_f32_16x16x32_bf16 v[44:47], v[160:163], v[200:203], v[44:47]
	v_mfma_f32_16x16x32_bf16 v[36:39], v[128:131], v[210:213], v[36:39]
	v_mfma_f32_16x16x32_bf16 v[28:31], v[160:163], v[210:213], v[28:31]
	v_mfma_f32_16x16x32_bf16 v[20:23], v[128:131], v[218:221], v[20:23]
	v_mfma_f32_16x16x32_bf16 v[12:15], v[160:163], v[218:221], v[12:15]
	v_mfma_f32_16x16x32_bf16 v[60:63], v[132:135], v[196:199], v[60:63]
	v_mfma_f32_16x16x32_bf16 v[56:59], v[164:167], v[196:199], v[56:59]
	v_mfma_f32_16x16x32_bf16 v[52:55], v[132:135], v[206:209], v[52:55]
	v_mfma_f32_16x16x32_bf16 v[44:47], v[164:167], v[206:209], v[44:47]
	v_mfma_f32_16x16x32_bf16 v[36:39], v[132:135], v[214:217], v[36:39]
	v_mfma_f32_16x16x32_bf16 v[28:31], v[164:167], v[214:217], v[28:31]
	v_mfma_f32_16x16x32_bf16 v[20:23], v[132:135], v[222:225], v[20:23]
	v_mfma_f32_16x16x32_bf16 v[12:15], v[164:167], v[222:225], v[12:15]

.Lkr_skip4:
	s_setprio 0
	s_barrier
	s_add_i32 s11, 0, 0x18000
	v_add_u32_e32 v144, s11, v170
	s_add_i32 s62, 0, 0x1c000
	s_and_b64 s[100:101], s[42:43], exec
	s_cbranch_scc0 .Lkr_dskip4
	ds_read_b128 v[128:131], v144
	ds_read_b128 v[132:135], v144 offset:1024
	ds_read_b128 v[160:163], v144 offset:2048
	ds_read_b128 v[164:167], v144 offset:3072
.Lkr_dskip4:
	v_add_u32_e32 v144, s62, v170
	s_add_u32 s60, s80, 0x80000
	s_addc_u32 s61, s81, 0
	s_mov_b32 m0, s84
	v_lshl_add_u64 v[232:233], s[60:61], 0, v[136:137]
	s_and_b64 s[100:101], s[42:43], exec
	s_cbranch_scc0 .Lkr_dskip5
	ds_read_b128 v[192:195], v173 offset:32768
	ds_read_b128 v[196:199], v173 offset:33792
	ds_read_b128 v[200:203], v173 offset:34816
	ds_read_b128 v[206:209], v173 offset:35840
	ds_read_b128 v[210:213], v173 offset:36864
	ds_read_b128 v[214:217], v173 offset:37888
	ds_read_b128 v[218:221], v173 offset:38912
	ds_read_b128 v[222:225], v173 offset:39936
.Lkr_dskip5:
	global_load_lds_dwordx4 v[232:233], off
	v_lshl_add_u64 v[232:233], s[60:61], 0, v[140:141]
	s_mov_b32 m0, s85
	s_nop 0
	global_load_lds_dwordx4 v[232:233], off
	s_waitcnt vmcnt(8)
	s_waitcnt lgkmcnt(0)
	s_barrier
	s_setprio 1
	s_waitcnt lgkmcnt(0)
	s_and_b64 s[100:101], s[42:43], exec
	s_cbranch_scc0 .Lkr_skip5
	v_mfma_f32_16x16x32_bf16 v[124:127], v[128:131], v[192:195], v[124:127]
	v_mfma_f32_16x16x32_bf16 v[120:123], v[160:163], v[192:195], v[120:123]
	v_mfma_f32_16x16x32_bf16 v[116:119], v[128:131], v[200:203], v[116:119]
	v_mfma_f32_16x16x32_bf16 v[108:111], v[160:163], v[200:203], v[108:111]
	v_mfma_f32_16x16x32_bf16 v[100:103], v[128:131], v[210:213], v[100:103]
	v_mfma_f32_16x16x32_bf16 v[92:95], v[160:163], v[210:213], v[92:95]
	v_mfma_f32_16x16x32_bf16 v[84:87], v[128:131], v[218:221], v[84:87]
	v_mfma_f32_16x16x32_bf16 v[76:79], v[160:163], v[218:221], v[76:79]
	v_mfma_f32_16x16x32_bf16 v[124:127], v[132:135], v[196:199], v[124:127]
	v_mfma_f32_16x16x32_bf16 v[120:123], v[164:167], v[196:199], v[120:123]
	v_mfma_f32_16x16x32_bf16 v[116:119], v[132:135], v[206:209], v[116:119]
	v_mfma_f32_16x16x32_bf16 v[108:111], v[164:167], v[206:209], v[108:111]
	v_mfma_f32_16x16x32_bf16 v[100:103], v[132:135], v[214:217], v[100:103]
	v_mfma_f32_16x16x32_bf16 v[92:95], v[164:167], v[214:217], v[92:95]
	v_mfma_f32_16x16x32_bf16 v[84:87], v[132:135], v[222:225], v[84:87]
	v_mfma_f32_16x16x32_bf16 v[76:79], v[164:167], v[222:225], v[76:79]

.Lkr_skip6:
	s_setprio 0
	s_barrier
	s_add_i32 s11, s11, s3
	v_lshl_add_u64 v[168:169], v[168:169], 0, s[38:39]
	s_mov_b32 m0, s11
	s_and_b64 s[100:101], s[42:43], exec
	s_cbranch_scc0 .Lkr_dskip6
	ds_read_b128 v[192:195], v173 offset:49152
	ds_read_b128 v[196:199], v173 offset:50176
	ds_read_b128 v[200:203], v173 offset:51200
	ds_read_b128 v[206:209], v173 offset:52224
	ds_read_b128 v[210:213], v173 offset:53248
	ds_read_b128 v[214:217], v173 offset:54272
	ds_read_b128 v[218:221], v173 offset:55296
	ds_read_b128 v[222:225], v173 offset:56320
.Lkr_dskip6:
	global_load_lds_dwordx4 v[168:169], off
	s_add_i32 m0, s11, 0x2000
	s_add_u32 s60, s78, 0x80080
	v_lshl_add_u64 v[168:169], v[226:227], 0, s[38:39]
	s_addc_u32 s61, s79, 0
	s_add_i32 s11, s62, s3
	global_load_lds_dwordx4 v[168:169], off
	v_lshl_add_u64 v[168:169], s[60:61], 0, v[138:139]
	s_mov_b32 m0, s11
	s_nop 0
	global_load_lds_dwordx4 v[168:169], off
	v_lshl_add_u64 v[168:169], s[60:61], 0, v[142:143]
	s_add_i32 m0, s11, 0x2000
	s_nop 0
	global_load_lds_dwordx4 v[168:169], off
	v_lshl_add_u64 v[168:169], v[228:229], 0, s[38:39]
	s_mov_b32 m0, s89
	s_nop 0
	global_load_lds_dwordx4 v[168:169], off
	v_lshl_add_u64 v[168:169], v[230:231], 0, s[38:39]
	s_mov_b32 m0, s90
	s_nop 0
	global_load_lds_dwordx4 v[168:169], off
	s_waitcnt vmcnt(8)
	s_waitcnt lgkmcnt(0)
	s_barrier
	s_setprio 1
	s_waitcnt lgkmcnt(0)
	s_and_b64 s[100:101], s[42:43], exec
	s_cbranch_scc0 .Lkr_skip7
	v_mfma_f32_16x16x32_bf16 v[60:63], v[128:131], v[192:195], v[60:63]
	v_mfma_f32_16x16x32_bf16 v[56:59], v[160:163], v[192:195], v[56:59]
	v_mfma_f32_16x16x32_bf16 v[52:55], v[128:131], v[200:203], v[52:55]
	v_mfma_f32_16x16x32_bf16 v[44:47], v[160:163], v[200:203], v[44:47]
	v_mfma_f32_16x16x32_bf16 v[36:39], v[128:131], v[210:213], v[36:39]
	v_mfma_f32_16x16x32_bf16 v[28:31], v[160:163], v[210:213], v[28:31]
	v_mfma_f32_16x16x32_bf16 v[20:23], v[128:131], v[218:221], v[20:23]
	v_mfma_f32_16x16x32_bf16 v[12:15], v[160:163], v[218:221], v[12:15]
	v_mfma_f32_16x16x32_bf16 v[60:63], v[132:135], v[196:199], v[60:63]
	v_mfma_f32_16x16x32_bf16 v[56:59], v[164:167], v[196:199], v[56:59]
	v_mfma_f32_16x16x32_bf16 v[52:55], v[132:135], v[206:209], v[52:55]
	v_mfma_f32_16x16x32_bf16 v[44:47], v[164:167], v[206:209], v[44:47]
	v_mfma_f32_16x16x32_bf16 v[36:39], v[132:135], v[214:217], v[36:39]
	v_mfma_f32_16x16x32_bf16 v[28:31], v[164:167], v[214:217], v[28:31]
	v_mfma_f32_16x16x32_bf16 v[20:23], v[132:135], v[222:225], v[20:23]
	v_mfma_f32_16x16x32_bf16 v[12:15], v[164:167], v[222:225], v[12:15]
